# all three multi-tile epilogues: sum-of-squares (and norm-weight) loads issued before the half-alignment barrier so their round trip overlaps the wait for the trailing half
# baseline (speedup 1.0000x reference)
; __device__ __forceinline__ float row_rstd(const float* ss, int row) {
;     const f32x4 a = *(const f32x4*)(ss + (size_t)row * 8), b = *(const f32x4*)(ss + (size_t)row * 8 + 4);
;     const float s = ((a[0] + a[1]) + (a[2] + a[3])) + ((b[0] + b[1]) + (b[2] + b[3]));
;     return 1.0f / sqrtf(s * (1.0f / 2048.0f) + 1e-6f);
;     __device__ __forceinline__ void operator()(f32x4 (&acc)[2][2][4][2], const Unit& u, int wr, int wc, int fr, int fq, PG8_LAS unsigned char* lds, int wid, int lane) const {
;     ...
;         const int grow0 = 254 * u.pm - 2;
;         { const int t = wid * 64 + lane; if (t < 256) { const int gr = grow0 + t; tbl[t] = (gr >= 0 && gr < 8192) ? row_rstd(ss, gr) : 0.f; } }
.LBB0_366:
	s_mul_i32 s98, s37, 0xfe
	s_add_i32 s98, s98, -2
	s_mov_b64 s[88:89], exec
	v_readlane_b32 s0, v252, 51
	v_readlane_b32 s1, v252, 52
	s_nop 0
	s_and_b64 exec, exec, s[0:1]
	v_add_u32_e32 v216, s98, v231
	v_cmp_gt_u32_e32 vcc, 0x2000, v216
	s_nop 1
	s_and_b64 exec, exec, vcc
	v_lshlrev_b32_e32 v217, 5, v216
	global_load_dwordx4 v[120:123], v217, s[28:29]
	global_load_dwordx4 v[124:127], v217, s[28:29] offset:16
	s_mov_b64 exec, s[88:89]
	v_readlane_b32 s0, v252, 42
	v_readlane_b32 s1, v252, 43
	s_and_b64 vcc, exec, s[0:1]
	s_cbranch_vccz .LBB0_368
	s_barrier
.LBB0_368:
	s_mul_i32 s72, s37, 0xfe
	s_add_i32 s72, s72, -2
	s_mov_b64 s[86:87], exec
	v_readlane_b32 s0, v252, 51
	v_readlane_b32 s1, v252, 52
	s_and_b64 s[0:1], s[86:87], s[0:1]
	s_movk_i32 s37, 0x2000
	s_mov_b64 exec, s[0:1]
	s_cbranch_execz .LBB0_372
	v_add_u32_e32 v216, s72, v231
	v_cmp_gt_u32_e32 vcc, s37, v216
	v_mov_b32_e32 v0, 0
	s_and_saveexec_b64 s[88:89], vcc
	s_cbranch_execz .LBB0_371
	s_mov_b32 s0, 0xf800000
	s_waitcnt vmcnt(0)
	v_mov_b32_e32 v128, v120
	v_mov_b32_e32 v129, v124
	v_mov_b32_e32 v124, v121
	v_mov_b32_e32 v120, v122
	v_mov_b32_e32 v121, v126
	v_mov_b32_e32 v126, v123
	v_pk_add_f32 v[122:123], v[128:129], v[124:125]
	v_pk_add_f32 v[120:121], v[120:121], v[126:127]
	s_nop 0
	v_pk_add_f32 v[120:121], v[122:123], v[120:121]
	s_nop 0
	v_add_f32_e32 v0, v120, v121
	v_fmamk_f32 v0, v0, 0x3a000000, v210
	v_mul_f32_e32 v120, 0x4f800000, v0
	v_cmp_gt_f32_e32 vcc, s0, v0
	s_nop 1
	v_cndmask_b32_e32 v0, v0, v120, vcc
	v_sqrt_f32_e32 v120, v0
	s_nop 0
	v_add_u32_e32 v121, -1, v120
	v_add_u32_e32 v122, 1, v120
	v_fma_f32 v123, -v121, v120, v0
	v_fma_f32 v124, -v122, v120, v0
	v_cmp_ge_f32_e64 s[0:1], 0, v123
	s_nop 1
	v_cndmask_b32_e64 v120, v120, v121, s[0:1]
	v_cmp_lt_f32_e64 s[0:1], 0, v124
	s_nop 1
	v_cndmask_b32_e64 v120, v120, v122, s[0:1]
	v_mul_f32_e32 v121, 0x37800000, v120
	v_cndmask_b32_e32 v120, v120, v121, vcc
	v_cmp_class_f32_e32 vcc, v0, v211
	s_nop 1
	v_cndmask_b32_e32 v0, v120, v0, vcc
	v_div_scale_f32 v120, s[0:1], v0, v0, 1.0
	v_rcp_f32_e32 v121, v120
	v_div_scale_f32 v122, vcc, 1.0, v0, 1.0
	v_fma_f32 v123, -v120, v121, 1.0
	v_fmac_f32_e32 v121, v123, v121
	v_mul_f32_e32 v123, v122, v121
	v_fma_f32 v124, -v120, v123, v122
	v_fmac_f32_e32 v123, v124, v121
	v_fma_f32 v120, -v120, v123, v122
	v_div_fmas_f32 v120, v120, v121, v123
	v_div_fixup_f32 v0, v120, v0, 1.0

; __device__ __forceinline__ float row_rstd(const float* ss, int row) {
;     const f32x4 a = *(const f32x4*)(ss + (size_t)row * 8), b = *(const f32x4*)(ss + (size_t)row * 8 + 4);
;     const float s = ((a[0] + a[1]) + (a[2] + a[3])) + ((b[0] + b[1]) + (b[2] + b[3]));
;     return 1.0f / sqrtf(s * (1.0f / 2048.0f) + 1e-6f);
;     __device__ __forceinline__ void operator()(const f32x4 (&acc)[2][2][4][2], const Unit& u, int wr, int wc, int fr, int fq, PG8_LAS unsigned char* lds, int wid, int lane) const {
;     ...
;         { const int t = wid * 64 + lane; if (t < 256) { const int col = u.pn * BM + t; float r = row_rstd(ss, col);
;             if (u.pm < 8) { const float lg = -log2f(1.0f - exp2f(-5.0f - (float)u.pm)); r *= exp2f(lg * (float)((col & 127) + 1)) * 0.0625f; } tbl[t] = r; } }
.LBB0_469:
	s_lshl_b32 s98, s37, 8
	s_and_saveexec_b64 s[40:41], s[2:3]
	v_add_u32_e32 v136, s98, v163
	v_ashrrev_i32_e32 v137, 31, v136
	v_lshlrev_b64 v[136:137], 5, v[136:137]
	v_lshl_add_u64 v[140:141], s[28:29], 0, v[136:137]
	global_load_dwordx4 v[136:139], v[140:141], off
	s_nop 0
	global_load_dwordx4 v[140:143], v[140:141], off offset:16
	s_or_b64 exec, exec, s[40:41]
	s_and_b64 vcc, exec, s[12:13]
	s_cbranch_vccz .LBB0_471
	s_barrier
.LBB0_471:
	s_lshl_b32 s38, s37, 8
	s_and_saveexec_b64 s[40:41], s[2:3]
	s_mov_b32 s37, 0xf800000
	s_cbranch_execz .LBB0_475
	s_cmp_gt_i32 s77, 7
	s_waitcnt vmcnt(0)
	v_mov_b32_e32 v144, v136
	v_mov_b32_e32 v145, v140
	v_mov_b32_e32 v140, v137
	v_mov_b32_e32 v136, v138
	v_mov_b32_e32 v137, v142
	v_mov_b32_e32 v142, v139
	v_pk_add_f32 v[138:139], v[144:145], v[140:141]
	v_pk_add_f32 v[136:137], v[136:137], v[142:143]
	s_nop 0
	v_pk_add_f32 v[136:137], v[138:139], v[136:137]
	s_nop 0
	v_add_f32_e32 v136, v136, v137
	v_fmamk_f32 v136, v136, 0x3a000000, v210
	v_mul_f32_e32 v137, 0x4f800000, v136
	v_cmp_gt_f32_e32 vcc, s37, v136
	s_nop 1
	v_cndmask_b32_e32 v136, v136, v137, vcc
	v_sqrt_f32_e32 v137, v136
	s_nop 0
	v_add_u32_e32 v138, -1, v137
	v_add_u32_e32 v139, 1, v137
	v_fma_f32 v140, -v138, v137, v136
	v_fma_f32 v141, -v139, v137, v136
	v_cmp_ge_f32_e64 s[0:1], 0, v140
	s_nop 1
	v_cndmask_b32_e64 v137, v137, v138, s[0:1]
	v_cmp_lt_f32_e64 s[0:1], 0, v141
	s_nop 1
	v_cndmask_b32_e64 v137, v137, v139, s[0:1]
	v_mul_f32_e32 v138, 0x37800000, v137
	v_cndmask_b32_e32 v137, v137, v138, vcc
	v_cmp_class_f32_e32 vcc, v136, v211
	s_nop 1
	v_cndmask_b32_e32 v136, v137, v136, vcc
	v_div_scale_f32 v137, s[0:1], v136, v136, 1.0
	v_rcp_f32_e32 v138, v137
	v_div_scale_f32 v139, vcc, 1.0, v136, 1.0
	v_fma_f32 v140, -v137, v138, 1.0
	v_fmac_f32_e32 v138, v140, v138
	v_mul_f32_e32 v140, v139, v138
	v_fma_f32 v141, -v137, v140, v139
	v_fmac_f32_e32 v140, v141, v138
	v_fma_f32 v137, -v137, v140, v139
	v_div_fmas_f32 v137, v137, v138, v140
	v_div_fixup_f32 v136, v137, v136, 1.0
	s_cbranch_scc1 .LBB0_474
	v_cvt_f32_i32_e32 v137, s77
	s_mov_b32 s0, 0xc2fc0000
	v_sub_f32_e32 v137, 0xc0a00000, v137
	v_cmp_gt_f32_e32 vcc, s0, v137
	s_and_b64 s[0:1], vcc, exec
	s_cselect_b32 s0, 0xffffffc0, 0
	v_cndmask_b32_e32 v138, 0, v221, vcc
	v_add_f32_e32 v137, v137, v138
	v_exp_f32_e32 v137, v137
	v_mov_b32_e32 v138, 0x42000000
	v_ldexp_f32 v137, v137, s0
	v_sub_f32_e32 v137, 1.0, v137
	s_mov_b32 s0, 0x800000
	v_cmp_gt_f32_e32 vcc, s0, v137
	s_and_b64 s[0:1], vcc, exec
	s_cselect_b32 s0, 32, 0
	v_ldexp_f32 v137, v137, s0
	v_log_f32_e32 v137, v137
	v_cndmask_b32_e32 v138, 0, v138, vcc
	s_mov_b32 s0, 0xc2fc0000
	v_sub_f32_e32 v137, v137, v138
	v_mul_f32_e64 v138, v164, -v137
	v_cmp_gt_f32_e32 vcc, s0, v138
	s_nop 1
	v_cndmask_b32_e32 v138, 0, v221, vcc
	v_fma_f32 v137, v164, -v137, v138
	v_exp_f32_e32 v137, v137
	v_not_b32_e32 v138, 63
	v_cndmask_b32_e32 v138, 0, v138, vcc
	v_ldexp_f32 v137, v137, v138
	v_mul_f32_e32 v137, 0x3d800000, v137
	v_mul_f32_e32 v136, v137, v136

; #define PG8_STAGE(bufoff, gbase, voff) do { _Pragma("unroll") for (int _i = 0; _i < 2; ++_i) \
;         __builtin_amdgcn_global_load_lds((const unsigned*)((const char*)(gbase) + (voff)[_i]), (PG8_LAS unsigned*)(lds + (bufoff) + ldsw + _i * 8192), 16, 0, 0); } while (0)
; #define PG8_LDA(dst, b, h) do { _Pragma("unroll") for (int m = 0; m < 4; ++m) _Pragma("unroll") for (int k = 0; k < 2; ++k) dst[m][k] = *(const PG8_LAS bf16x8*)(lds + PG8_SA(b, h) + aoff + m * 2048 + k * 1024); } while (0)
; #define PG8_LDB(dst, b, h) do { _Pragma("unroll") for (int n = 0; n < 2; ++n) _Pragma("unroll") for (int k = 0; k < 2; ++k) dst[n][k] = *(const PG8_LAS bf16x8*)(lds + PG8_SB(b, h) + boff + n * 2048 + k * 1024); } while (0)
; #define PG8_MMA(ai, bj, At, Bt) do { __builtin_amdgcn_s_setprio(1); _Pragma("unroll") for (int m = 0; m < 4; ++m) _Pragma("unroll") for (int n = 0; n < 2; ++n) _Pragma("unroll") for (int k = 0; k < 2; ++k) \
;         acc[ai][bj][m][n] = __builtin_amdgcn_mfma_f32_16x16x32_bf16(Bt[n][k], At[m][k], acc[ai][bj][m][n], 0, 0, 0); __builtin_amdgcn_s_setprio(0); } while (0)
; #define PG8_WAIT_V(n) asm volatile("s_waitcnt vmcnt(" #n ")" ::: "memory")
; template <class Epi, class Sched, bool ALIGN_EPI = false, bool SP2 = false>
; __device__ __forceinline__ void gemm_phase(PG8_LAS unsigned char* lds, const Gemm g, const Sched& S, const Epi& E) {
;     ...
;             PG8_LDB(B0, 0, 0); PG8_LDB(B1, 0, 1); PG8_SCHED; PG8_LDA(At, 0, 0); PG8_STAGE(PG8_SA(1, 1), a1 + hstep, voffA);
;             PG8_WAIT_V(8); PG8_WAIT_L(0); PG8_BAR; PG8_MMA(0, 0, At, B0); PG8_MMA(0, 1, At, B1); PG8_BAR; PG8_SCHED;
;             PG8_LDA(At, 0, 1); PG8_STAGE(PG8_SB(0, 0), b2, voffB); PG8_STAGE(PG8_SB(0, 1), b2 + hstep, voffB); PG8_STAGE(PG8_SA(0, 0), a2, voffA);
;             PG8_WAIT_V(8); PG8_WAIT_L(0); PG8_BAR; PG8_MMA(1, 0, At, B0); PG8_MMA(1, 1, At, B1); PG8_BAR; PG8_SCHED;
;             PG8_LDB(B0, 1, 0); PG8_LDB(B1, 1, 1); PG8_SCHED; PG8_LDA(At, 1, 0); PG8_STAGE(PG8_SA(0, 1), a2 + hstep, voffA);
;             PG8_WAIT_V(8); PG8_WAIT_L(0); PG8_BAR; PG8_MMA(0, 0, At, B0); PG8_MMA(0, 1, At, B1); PG8_BAR; PG8_SCHED;
;             PG8_LDA(At, 1, 1); PG8_STAGE(PG8_SB(1, 0), b3, voffB); PG8_STAGE(PG8_SB(1, 1), b3 + hstep, voffB); PG8_STAGE(PG8_SA(1, 0), a3, voffA);
;             PG8_WAIT_V(8); PG8_WAIT_L(0); PG8_BAR; PG8_MMA(1, 0, At, B0); PG8_MMA(1, 1, At, B1); PG8_BAR; PG8_SCHED;
.LBB0_501:
	s_add_i32 s80, s4, 2
	s_add_u32 s81, s0, 0x80
	s_addc_u32 s5, s1, 0
	s_cmp_eq_u32 s33, s4
	s_cselect_b32 s5, s23, s5
	s_cselect_b32 s4, s22, s81
	s_cselect_b32 s83, s41, s43
	s_cselect_b32 s82, s40, s42
	s_add_i32 s81, 0, 0x14000
	v_add_u32_e32 v148, s19, v164
	v_add_u32_e32 v162, s81, v164
	ds_read_b128 v[136:139], v148
	ds_read_b128 v[140:143], v148 offset:1024
	ds_read_b128 v[144:147], v148 offset:2048
	ds_read_b128 v[148:151], v148 offset:3072
	ds_read_b128 v[174:177], v162
	ds_read_b128 v[178:181], v162 offset:1024
	ds_read_b128 v[184:187], v162 offset:2048
	ds_read_b128 v[188:191], v162 offset:3072
	v_lshl_add_u64 v[162:163], s[0:1], 0, v[158:159]
	s_add_i32 m0, s45, 0xc000
	ds_read_b128 v[192:195], v170
	ds_read_b128 v[196:199], v170 offset:1024
	ds_read_b128 v[200:203], v170 offset:2048
	ds_read_b128 v[204:207], v170 offset:3072
	ds_read_b128 v[230:233], v170 offset:4096
	ds_read_b128 v[234:237], v170 offset:5120
	ds_read_b128 v[238:241], v170 offset:6144
	ds_read_b128 v[242:245], v170 offset:7168
	global_load_lds_dwordx4 v[162:163], off
	v_lshl_add_u64 v[162:163], s[0:1], 0, v[160:161]
	s_add_i32 m0, s45, 0xe000
	s_nop 0
	global_load_lds_dwordx4 v[162:163], off
	s_waitcnt vmcnt(8)
	s_waitcnt lgkmcnt(0)
	s_barrier
	s_setprio 1
	s_waitcnt lgkmcnt(0)
	v_mfma_f32_16x16x32_bf16 v[132:135], v[136:139], v[192:195], v[132:135]
	v_mfma_f32_16x16x32_bf16 v[132:135], v[140:143], v[196:199], v[132:135]
	v_mfma_f32_16x16x32_bf16 v[116:119], v[136:139], v[200:203], v[116:119]
	v_mfma_f32_16x16x32_bf16 v[116:119], v[140:143], v[204:207], v[116:119]
	v_mfma_f32_16x16x32_bf16 v[100:103], v[136:139], v[230:233], v[100:103]
	v_mfma_f32_16x16x32_bf16 v[100:103], v[140:143], v[234:237], v[100:103]
	v_mfma_f32_16x16x32_bf16 v[84:87], v[136:139], v[238:241], v[84:87]
	v_mfma_f32_16x16x32_bf16 v[84:87], v[140:143], v[242:245], v[84:87]
	v_mfma_f32_16x16x32_bf16 v[80:83], v[144:147], v[238:241], v[80:83]
	v_mfma_f32_16x16x32_bf16 v[80:83], v[148:151], v[242:245], v[80:83]
	v_mfma_f32_16x16x32_bf16 v[96:99], v[144:147], v[230:233], v[96:99]
	v_mfma_f32_16x16x32_bf16 v[96:99], v[148:151], v[234:237], v[96:99]
	v_mfma_f32_16x16x32_bf16 v[112:115], v[144:147], v[200:203], v[112:115]
	v_mfma_f32_16x16x32_bf16 v[112:115], v[148:151], v[204:207], v[112:115]
	v_mfma_f32_16x16x32_bf16 v[128:131], v[144:147], v[192:195], v[128:131]
	v_mfma_f32_16x16x32_bf16 v[128:131], v[148:151], v[196:199], v[128:131]
	s_setprio 0
	s_setprio 1
	v_mfma_f32_16x16x32_bf16 v[124:127], v[174:177], v[192:195], v[124:127]
	v_mfma_f32_16x16x32_bf16 v[124:127], v[178:181], v[196:199], v[124:127]
	v_mfma_f32_16x16x32_bf16 v[108:111], v[174:177], v[200:203], v[108:111]
	v_mfma_f32_16x16x32_bf16 v[108:111], v[178:181], v[204:207], v[108:111]
	v_mfma_f32_16x16x32_bf16 v[92:95], v[174:177], v[230:233], v[92:95]
	v_mfma_f32_16x16x32_bf16 v[92:95], v[178:181], v[234:237], v[92:95]
	v_mfma_f32_16x16x32_bf16 v[76:79], v[174:177], v[238:241], v[76:79]
	v_mfma_f32_16x16x32_bf16 v[76:79], v[178:181], v[242:245], v[76:79]
	v_mfma_f32_16x16x32_bf16 v[72:75], v[184:187], v[238:241], v[72:75]
	v_mfma_f32_16x16x32_bf16 v[72:75], v[188:191], v[242:245], v[72:75]
	v_mfma_f32_16x16x32_bf16 v[88:91], v[184:187], v[230:233], v[88:91]
	v_mfma_f32_16x16x32_bf16 v[88:91], v[188:191], v[234:237], v[88:91]
	v_mfma_f32_16x16x32_bf16 v[104:107], v[184:187], v[200:203], v[104:107]
	v_mfma_f32_16x16x32_bf16 v[104:107], v[188:191], v[204:207], v[104:107]
	v_mfma_f32_16x16x32_bf16 v[120:123], v[184:187], v[192:195], v[120:123]
	v_mfma_f32_16x16x32_bf16 v[120:123], v[188:191], v[196:199], v[120:123]
	s_setprio 0
	s_barrier
	s_add_i32 s84, s19, s44
	v_lshl_add_u64 v[162:163], s[82:83], 0, v[152:153]
	s_mov_b32 m0, s84
	ds_read_b128 v[192:195], v170 offset:16384
	ds_read_b128 v[196:199], v170 offset:17408
	ds_read_b128 v[200:203], v170 offset:18432
	ds_read_b128 v[204:207], v170 offset:19456
	ds_read_b128 v[230:233], v170 offset:20480
	ds_read_b128 v[234:237], v170 offset:21504
	ds_read_b128 v[238:241], v170 offset:22528
	ds_read_b128 v[242:245], v170 offset:23552
	global_load_lds_dwordx4 v[162:163], off
	s_add_i32 m0, s84, 0x2000
	v_lshl_add_u64 v[208:209], s[82:83], 0, v[156:157]
	s_add_u32 s82, s82, s48
	s_addc_u32 s83, s83, s49
	s_add_i32 s81, s81, s44
	global_load_lds_dwordx4 v[208:209], off
	v_lshl_add_u64 v[246:247], s[82:83], 0, v[152:153]
	s_mov_b32 m0, s81
	v_lshl_add_u64 v[248:249], s[82:83], 0, v[156:157]
	global_load_lds_dwordx4 v[246:247], off
	s_add_i32 m0, s81, 0x2000
	v_lshl_add_u64 v[216:217], s[4:5], 0, v[2:3]
	global_load_lds_dwordx4 v[248:249], off
	s_mov_b32 m0, s45
	v_lshl_add_u64 v[224:225], s[4:5], 0, v[154:155]
	global_load_lds_dwordx4 v[216:217], off
	s_mov_b32 m0, s46
	s_nop 0
	global_load_lds_dwordx4 v[224:225], off
	s_waitcnt vmcnt(8)
	s_waitcnt lgkmcnt(0)
	s_barrier
; #define PG8_STAGE(bufoff, gbase, voff) do { _Pragma("unroll") for (int _i = 0; _i < 2; ++_i) \
;         __builtin_amdgcn_global_load_lds((const unsigned*)((const char*)(gbase) + (voff)[_i]), (PG8_LAS unsigned*)(lds + (bufoff) + ldsw + _i * 8192), 16, 0, 0); } while (0)
; #define PG8_LDA(dst, b, h) do { _Pragma("unroll") for (int m = 0; m < 4; ++m) _Pragma("unroll") for (int k = 0; k < 2; ++k) dst[m][k] = *(const PG8_LAS bf16x8*)(lds + PG8_SA(b, h) + aoff + m * 2048 + k * 1024); } while (0)
; #define PG8_LDB(dst, b, h) do { _Pragma("unroll") for (int n = 0; n < 2; ++n) _Pragma("unroll") for (int k = 0; k < 2; ++k) dst[n][k] = *(const PG8_LAS bf16x8*)(lds + PG8_SB(b, h) + boff + n * 2048 + k * 1024); } while (0)
; #define PG8_MMA(ai, bj, At, Bt) do { __builtin_amdgcn_s_setprio(1); _Pragma("unroll") for (int m = 0; m < 4; ++m) _Pragma("unroll") for (int n = 0; n < 2; ++n) _Pragma("unroll") for (int k = 0; k < 2; ++k) \
;         acc[ai][bj][m][n] = __builtin_amdgcn_mfma_f32_16x16x32_bf16(Bt[n][k], At[m][k], acc[ai][bj][m][n], 0, 0, 0); __builtin_amdgcn_s_setprio(0); } while (0)
; #define PG8_WAIT_V(n) asm volatile("s_waitcnt vmcnt(" #n ")" ::: "memory")
; #define PG8_WAIT_L(n) asm volatile("s_waitcnt lgkmcnt(" #n ")" ::: "memory")
; #define PG8_BAR __builtin_amdgcn_s_barrier()
; template <class Epi, class Sched, bool ALIGN_EPI = false, bool SP2 = false>
; __device__ __forceinline__ void gemm_phase(PG8_LAS unsigned char* lds, const Gemm g, const Sched& S, const Epi& E) {
;     ...
;             PG8_WAIT_V(8); PG8_WAIT_L(0); PG8_BAR; PG8_MMA(0, 0, At, B0); PG8_MMA(0, 1, At, B1); PG8_BAR; PG8_SCHED;
;             PG8_LDA(At, 0, 1); PG8_STAGE(PG8_SB(0, 0), b2, voffB); PG8_STAGE(PG8_SB(0, 1), b2 + hstep, voffB); PG8_STAGE(PG8_SA(0, 0), a2, voffA);
;             PG8_WAIT_V(8); PG8_WAIT_L(0); PG8_BAR; PG8_MMA(1, 0, At, B0); PG8_MMA(1, 1, At, B1); PG8_BAR; PG8_SCHED;
;             PG8_LDB(B0, 1, 0); PG8_LDB(B1, 1, 1); PG8_SCHED; PG8_LDA(At, 1, 0); PG8_STAGE(PG8_SA(0, 1), a2 + hstep, voffA);
;             PG8_WAIT_V(8); PG8_WAIT_L(0); PG8_BAR; PG8_MMA(0, 0, At, B0); PG8_MMA(0, 1, At, B1); PG8_BAR; PG8_SCHED;
;             PG8_LDA(At, 1, 1); PG8_STAGE(PG8_SB(1, 0), b3, voffB); PG8_STAGE(PG8_SB(1, 1), b3 + hstep, voffB); PG8_STAGE(PG8_SA(1, 0), a3, voffA);
;             PG8_WAIT_V(8); PG8_WAIT_L(0); PG8_BAR; PG8_MMA(1, 0, At, B0); PG8_MMA(1, 1, At, B1); PG8_BAR; PG8_SCHED;
	s_setprio 1
	s_waitcnt lgkmcnt(0)
	v_mfma_f32_16x16x32_bf16 v[68:71], v[136:139], v[192:195], v[68:71]
	v_mfma_f32_16x16x32_bf16 v[68:71], v[140:143], v[196:199], v[68:71]
	v_mfma_f32_16x16x32_bf16 v[52:55], v[136:139], v[200:203], v[52:55]
	v_mfma_f32_16x16x32_bf16 v[52:55], v[140:143], v[204:207], v[52:55]
	v_mfma_f32_16x16x32_bf16 v[36:39], v[136:139], v[230:233], v[36:39]
	v_mfma_f32_16x16x32_bf16 v[36:39], v[140:143], v[234:237], v[36:39]
	v_mfma_f32_16x16x32_bf16 v[20:23], v[136:139], v[238:241], v[20:23]
	v_mfma_f32_16x16x32_bf16 v[20:23], v[140:143], v[242:245], v[20:23]
	v_mfma_f32_16x16x32_bf16 v[16:19], v[144:147], v[238:241], v[16:19]
	v_mfma_f32_16x16x32_bf16 v[16:19], v[148:151], v[242:245], v[16:19]
	v_mfma_f32_16x16x32_bf16 v[32:35], v[144:147], v[230:233], v[32:35]
	v_mfma_f32_16x16x32_bf16 v[32:35], v[148:151], v[234:237], v[32:35]
	v_mfma_f32_16x16x32_bf16 v[48:51], v[144:147], v[200:203], v[48:51]
	v_mfma_f32_16x16x32_bf16 v[48:51], v[148:151], v[204:207], v[48:51]
	v_mfma_f32_16x16x32_bf16 v[64:67], v[144:147], v[192:195], v[64:67]
	v_mfma_f32_16x16x32_bf16 v[64:67], v[148:151], v[196:199], v[64:67]
	s_setprio 0
	s_setprio 1
	v_mfma_f32_16x16x32_bf16 v[60:63], v[174:177], v[192:195], v[60:63]
	v_mfma_f32_16x16x32_bf16 v[60:63], v[178:181], v[196:199], v[60:63]
	v_mfma_f32_16x16x32_bf16 v[44:47], v[174:177], v[200:203], v[44:47]
	v_mfma_f32_16x16x32_bf16 v[44:47], v[178:181], v[204:207], v[44:47]
	v_mfma_f32_16x16x32_bf16 v[28:31], v[174:177], v[230:233], v[28:31]
	v_mfma_f32_16x16x32_bf16 v[28:31], v[178:181], v[234:237], v[28:31]
	v_mfma_f32_16x16x32_bf16 v[12:15], v[174:177], v[238:241], v[12:15]
	v_mfma_f32_16x16x32_bf16 v[12:15], v[178:181], v[242:245], v[12:15]
	v_mfma_f32_16x16x32_bf16 v[8:11], v[184:187], v[238:241], v[8:11]
	v_mfma_f32_16x16x32_bf16 v[8:11], v[188:191], v[242:245], v[8:11]
	v_mfma_f32_16x16x32_bf16 v[24:27], v[184:187], v[230:233], v[24:27]
	v_mfma_f32_16x16x32_bf16 v[24:27], v[188:191], v[234:237], v[24:27]
	v_mfma_f32_16x16x32_bf16 v[40:43], v[184:187], v[200:203], v[40:43]
	v_mfma_f32_16x16x32_bf16 v[40:43], v[188:191], v[204:207], v[40:43]
	v_mfma_f32_16x16x32_bf16 v[56:59], v[184:187], v[192:195], v[56:59]
	v_mfma_f32_16x16x32_bf16 v[56:59], v[188:191], v[196:199], v[56:59]
	s_setprio 0
	s_barrier
	s_add_i32 s81, 0, 0x1c000
	v_add_u32_e32 v148, s91, v164
	v_add_u32_e32 v173, s81, v164
	ds_read_b128 v[136:139], v148
	ds_read_b128 v[140:143], v148 offset:1024
	ds_read_b128 v[144:147], v148 offset:2048
	ds_read_b128 v[148:151], v148 offset:3072
	ds_read_b128 v[174:177], v173
	ds_read_b128 v[178:181], v173 offset:1024
	ds_read_b128 v[184:187], v173 offset:2048
	ds_read_b128 v[188:191], v173 offset:3072
	s_add_u32 s4, s4, s48
	s_addc_u32 s5, s5, s49
	s_mov_b32 m0, s47
	v_lshl_add_u64 v[226:227], s[4:5], 0, v[2:3]
	ds_read_b128 v[192:195], v170 offset:32768
	ds_read_b128 v[196:199], v170 offset:33792
	ds_read_b128 v[200:203], v170 offset:34816
	ds_read_b128 v[204:207], v170 offset:35840
	ds_read_b128 v[230:233], v170 offset:36864
	ds_read_b128 v[234:237], v170 offset:37888
	ds_read_b128 v[238:241], v170 offset:38912
	ds_read_b128 v[242:245], v170 offset:39936
	global_load_lds_dwordx4 v[226:227], off
	v_lshl_add_u64 v[226:227], s[4:5], 0, v[154:155]
	s_mov_b32 m0, s52
	s_nop 0
	global_load_lds_dwordx4 v[226:227], off
	s_waitcnt vmcnt(8)
	s_waitcnt lgkmcnt(0)
	s_barrier
	s_setprio 1
	s_waitcnt lgkmcnt(0)
	v_mfma_f32_16x16x32_bf16 v[132:135], v[136:139], v[192:195], v[132:135]
	v_mfma_f32_16x16x32_bf16 v[132:135], v[140:143], v[196:199], v[132:135]
	v_mfma_f32_16x16x32_bf16 v[116:119], v[136:139], v[200:203], v[116:119]
	v_mfma_f32_16x16x32_bf16 v[116:119], v[140:143], v[204:207], v[116:119]
	v_mfma_f32_16x16x32_bf16 v[100:103], v[136:139], v[230:233], v[100:103]
	v_mfma_f32_16x16x32_bf16 v[100:103], v[140:143], v[234:237], v[100:103]
	v_mfma_f32_16x16x32_bf16 v[84:87], v[136:139], v[238:241], v[84:87]
	v_mfma_f32_16x16x32_bf16 v[84:87], v[140:143], v[242:245], v[84:87]
	v_mfma_f32_16x16x32_bf16 v[80:83], v[144:147], v[238:241], v[80:83]
	v_mfma_f32_16x16x32_bf16 v[80:83], v[148:151], v[242:245], v[80:83]
	v_mfma_f32_16x16x32_bf16 v[96:99], v[144:147], v[230:233], v[96:99]
	v_mfma_f32_16x16x32_bf16 v[96:99], v[148:151], v[234:237], v[96:99]
	v_mfma_f32_16x16x32_bf16 v[112:115], v[144:147], v[200:203], v[112:115]
	v_mfma_f32_16x16x32_bf16 v[112:115], v[148:151], v[204:207], v[112:115]
	v_mfma_f32_16x16x32_bf16 v[128:131], v[144:147], v[192:195], v[128:131]
	v_mfma_f32_16x16x32_bf16 v[128:131], v[148:151], v[196:199], v[128:131]
	s_setprio 0
	s_setprio 1
	v_mfma_f32_16x16x32_bf16 v[124:127], v[174:177], v[192:195], v[124:127]
	v_mfma_f32_16x16x32_bf16 v[124:127], v[178:181], v[196:199], v[124:127]
	v_mfma_f32_16x16x32_bf16 v[108:111], v[174:177], v[200:203], v[108:111]
	v_mfma_f32_16x16x32_bf16 v[108:111], v[178:181], v[204:207], v[108:111]
	v_mfma_f32_16x16x32_bf16 v[92:95], v[174:177], v[230:233], v[92:95]
	v_mfma_f32_16x16x32_bf16 v[92:95], v[178:181], v[234:237], v[92:95]
	v_mfma_f32_16x16x32_bf16 v[76:79], v[174:177], v[238:241], v[76:79]
	v_mfma_f32_16x16x32_bf16 v[76:79], v[178:181], v[242:245], v[76:79]
	v_mfma_f32_16x16x32_bf16 v[72:75], v[184:187], v[238:241], v[72:75]
	v_mfma_f32_16x16x32_bf16 v[72:75], v[188:191], v[242:245], v[72:75]
	v_mfma_f32_16x16x32_bf16 v[88:91], v[184:187], v[230:233], v[88:91]
	v_mfma_f32_16x16x32_bf16 v[88:91], v[188:191], v[234:237], v[88:91]
	v_mfma_f32_16x16x32_bf16 v[104:107], v[184:187], v[200:203], v[104:107]
	v_mfma_f32_16x16x32_bf16 v[104:107], v[188:191], v[204:207], v[104:107]
	v_mfma_f32_16x16x32_bf16 v[120:123], v[184:187], v[192:195], v[120:123]
	v_mfma_f32_16x16x32_bf16 v[120:123], v[188:191], v[196:199], v[120:123]
	s_setprio 0
	s_barrier
; #define PG8_LAS __attribute__((address_space(3)))
; #define PG8_STAGE(bufoff, gbase, voff) do { _Pragma("unroll") for (int _i = 0; _i < 2; ++_i) \
;         __builtin_amdgcn_global_load_lds((const unsigned*)((const char*)(gbase) + (voff)[_i]), (PG8_LAS unsigned*)(lds + (bufoff) + ldsw + _i * 8192), 16, 0, 0); } while (0)
; #define PG8_LDA(dst, b, h) do { _Pragma("unroll") for (int m = 0; m < 4; ++m) _Pragma("unroll") for (int k = 0; k < 2; ++k) dst[m][k] = *(const PG8_LAS bf16x8*)(lds + PG8_SA(b, h) + aoff + m * 2048 + k * 1024); } while (0)
; #define PG8_MMA(ai, bj, At, Bt) do { __builtin_amdgcn_s_setprio(1); _Pragma("unroll") for (int m = 0; m < 4; ++m) _Pragma("unroll") for (int n = 0; n < 2; ++n) _Pragma("unroll") for (int k = 0; k < 2; ++k) \
;         acc[ai][bj][m][n] = __builtin_amdgcn_mfma_f32_16x16x32_bf16(Bt[n][k], At[m][k], acc[ai][bj][m][n], 0, 0, 0); __builtin_amdgcn_s_setprio(0); } while (0)
; #define PG8_WAIT_V(n) asm volatile("s_waitcnt vmcnt(" #n ")" ::: "memory")
; #define PG8_WAIT_L(n) asm volatile("s_waitcnt lgkmcnt(" #n ")" ::: "memory")
;     __device__ __forceinline__ void operator()(const f32x4 (&acc)[2][2][4][2], const Unit& u, int wr, int wc, int fr, int fq, PG8_LAS unsigned char* lds, int wid, int lane) const {
;         const int colt = u.pn * BM; const int col0 = colt + wc * 32 + 8 * fq;
;         PG8_LAS float* tbl = (PG8_LAS float*)(lds + 131072 + 10240);
;         PG8_LAS unsigned char* st = lds + 131072 + wid * 1280;
;         { const int t = wid * 64 + lane; if (t < 256) tbl[t] = row_rstd(ss, u.pm * BM + t); }
;         f32x4 bv[2][2];
; #pragma unroll
;         for (int bj = 0; bj < 2; ++bj)
; #pragma unroll
;             for (int n = 0; n < 2; ++n) bv[bj][n] = bias ? *(const f32x4*)(bias + col0 + bj * HALF + 4 * n) : (f32x4){0.f, 0.f, 0.f, 0.f};
; template <class Epi, class Sched, bool ALIGN_EPI = false, bool SP2 = false>
; __device__ __forceinline__ void gemm_phase(PG8_LAS unsigned char* lds, const Gemm g, const Sched& S, const Epi& E) {
;     ...
;             PG8_WAIT_V(8); PG8_WAIT_L(0); PG8_BAR; PG8_MMA(0, 0, At, B0); PG8_MMA(0, 1, At, B1); PG8_BAR; PG8_SCHED;
;             PG8_LDA(At, 1, 1); PG8_STAGE(PG8_SB(1, 0), b3, voffB); PG8_STAGE(PG8_SB(1, 1), b3 + hstep, voffB); PG8_STAGE(PG8_SA(1, 0), a3, voffA);
;             PG8_WAIT_V(8); PG8_WAIT_L(0); PG8_BAR; PG8_MMA(1, 0, At, B0); PG8_MMA(1, 1, At, B1); PG8_BAR; PG8_SCHED;
	s_add_i32 s4, s91, s44
	v_lshl_add_u64 v[162:163], v[162:163], 0, s[24:25]
	s_mov_b32 m0, s4
	ds_read_b128 v[192:195], v170 offset:49152
	ds_read_b128 v[196:199], v170 offset:50176
	ds_read_b128 v[200:203], v170 offset:51200
	ds_read_b128 v[204:207], v170 offset:52224
	ds_read_b128 v[230:233], v170 offset:53248
	ds_read_b128 v[234:237], v170 offset:54272
	ds_read_b128 v[238:241], v170 offset:55296
	ds_read_b128 v[242:245], v170 offset:56320
	global_load_lds_dwordx4 v[162:163], off
	v_lshl_add_u64 v[162:163], v[208:209], 0, s[24:25]
	s_add_i32 m0, s4, 0x2000
	s_add_i32 s4, s81, s44
	global_load_lds_dwordx4 v[162:163], off
	v_lshl_add_u64 v[162:163], v[246:247], 0, s[24:25]
	s_mov_b32 m0, s4
	s_nop 0
	global_load_lds_dwordx4 v[162:163], off
	v_lshl_add_u64 v[162:163], v[248:249], 0, s[24:25]
	s_add_i32 m0, s4, 0x2000
	s_nop 0
	global_load_lds_dwordx4 v[162:163], off
	v_lshl_add_u64 v[162:163], v[216:217], 0, s[24:25]
	s_mov_b32 m0, s53
	s_nop 0
	global_load_lds_dwordx4 v[162:163], off
	v_lshl_add_u64 v[162:163], v[224:225], 0, s[24:25]
	s_mov_b32 m0, s72
	s_nop 0
	global_load_lds_dwordx4 v[162:163], off
	s_waitcnt vmcnt(8)
	s_waitcnt lgkmcnt(0)
	s_barrier
	s_setprio 1
	s_waitcnt lgkmcnt(0)
	v_mfma_f32_16x16x32_bf16 v[68:71], v[136:139], v[192:195], v[68:71]
	v_mfma_f32_16x16x32_bf16 v[68:71], v[140:143], v[196:199], v[68:71]
	v_mfma_f32_16x16x32_bf16 v[52:55], v[136:139], v[200:203], v[52:55]
	v_mfma_f32_16x16x32_bf16 v[52:55], v[140:143], v[204:207], v[52:55]
	v_mfma_f32_16x16x32_bf16 v[36:39], v[136:139], v[230:233], v[36:39]
	v_mfma_f32_16x16x32_bf16 v[36:39], v[140:143], v[234:237], v[36:39]
	v_mfma_f32_16x16x32_bf16 v[20:23], v[136:139], v[238:241], v[20:23]
	v_mfma_f32_16x16x32_bf16 v[20:23], v[140:143], v[242:245], v[20:23]
	v_mfma_f32_16x16x32_bf16 v[16:19], v[144:147], v[238:241], v[16:19]
	v_mfma_f32_16x16x32_bf16 v[16:19], v[148:151], v[242:245], v[16:19]
	v_mfma_f32_16x16x32_bf16 v[32:35], v[144:147], v[230:233], v[32:35]
	v_mfma_f32_16x16x32_bf16 v[32:35], v[148:151], v[234:237], v[32:35]
	v_mfma_f32_16x16x32_bf16 v[48:51], v[144:147], v[200:203], v[48:51]
	v_mfma_f32_16x16x32_bf16 v[48:51], v[148:151], v[204:207], v[48:51]
	v_mfma_f32_16x16x32_bf16 v[64:67], v[144:147], v[192:195], v[64:67]
	v_mfma_f32_16x16x32_bf16 v[64:67], v[148:151], v[196:199], v[64:67]
	s_setprio 0
	s_setprio 1
	v_mfma_f32_16x16x32_bf16 v[60:63], v[174:177], v[192:195], v[60:63]
	v_mfma_f32_16x16x32_bf16 v[60:63], v[178:181], v[196:199], v[60:63]
	v_mfma_f32_16x16x32_bf16 v[44:47], v[174:177], v[200:203], v[44:47]
	v_mfma_f32_16x16x32_bf16 v[44:47], v[178:181], v[204:207], v[44:47]
	v_mfma_f32_16x16x32_bf16 v[28:31], v[174:177], v[230:233], v[28:31]
	v_mfma_f32_16x16x32_bf16 v[28:31], v[178:181], v[234:237], v[28:31]
	v_mfma_f32_16x16x32_bf16 v[12:15], v[174:177], v[238:241], v[12:15]
	v_mfma_f32_16x16x32_bf16 v[12:15], v[178:181], v[242:245], v[12:15]
	v_mfma_f32_16x16x32_bf16 v[8:11], v[184:187], v[238:241], v[8:11]
	v_mfma_f32_16x16x32_bf16 v[8:11], v[188:191], v[242:245], v[8:11]
	v_mfma_f32_16x16x32_bf16 v[24:27], v[184:187], v[230:233], v[24:27]
	v_mfma_f32_16x16x32_bf16 v[24:27], v[188:191], v[234:237], v[24:27]
	v_mfma_f32_16x16x32_bf16 v[40:43], v[184:187], v[200:203], v[40:43]
	v_mfma_f32_16x16x32_bf16 v[40:43], v[188:191], v[204:207], v[40:43]
	v_mfma_f32_16x16x32_bf16 v[56:59], v[184:187], v[192:195], v[56:59]
	v_mfma_f32_16x16x32_bf16 v[56:59], v[188:191], v[196:199], v[56:59]
	s_setprio 0
	s_barrier
	s_add_u32 s0, s0, 0x100
	s_addc_u32 s1, s1, 0
	s_add_u32 s42, s42, 0x100
	s_addc_u32 s43, s43, 0
	s_cmp_ge_u32 s80, s9
	s_mov_b32 s4, s80
	s_cbranch_scc0 .LBB0_501
.LBB0_502:
	s_lshl_b32 s0, s79, 8
	v_or_b32_e32 v136, s0, v165
	v_readlane_b32 s4, v252, 47
	v_ashrrev_i32_e32 v137, 31, v136
	v_readlane_b32 s5, v252, 48
	s_andn2_b64 vcc, exec, s[10:11]
	v_mov_b32_e32 v144, 0
	v_lshl_add_u64 v[162:163], v[136:137], 2, s[4:5]
	v_cndmask_b32_e64 v137, 0, 1, s[10:11]
	v_mov_b32_e32 v136, 0
	v_cmp_ne_u32_e64 s[4:5], 1, v137
	v_mov_b32_e32 v145, 0
	v_mov_b32_e32 v146, 0
	v_mov_b32_e32 v147, 0
	s_cbranch_vccnz .LBB0_508
	global_load_dwordx4 v[144:147], v[162:163], off

; __device__ __forceinline__ float row_rstd(const float* ss, int row) {
;     const f32x4 a = *(const f32x4*)(ss + (size_t)row * 8), b = *(const f32x4*)(ss + (size_t)row * 8 + 4);
;     const float s = ((a[0] + a[1]) + (a[2] + a[3])) + ((b[0] + b[1]) + (b[2] + b[3]));
;     return 1.0f / sqrtf(s * (1.0f / 2048.0f) + 1e-6f);
;     __device__ __forceinline__ void operator()(const f32x4 (&acc)[2][2][4][2], const Unit& u, int wr, int wc, int fr, int fq, PG8_LAS unsigned char* lds, int wid, int lane) const {
;     ...
;         { const int t = wid * 64 + lane; if (t < 256) tbl[t] = row_rstd(ss, u.pm * BM + t); }
.Lmy_ssb:
	s_or_b64 exec, exec, s[4:5]
	s_and_b64 vcc, exec, s[12:13]
	s_cbranch_vccz .LBB0_504
	s_barrier
.LBB0_504:
	s_and_saveexec_b64 s[4:5], s[38:39]
	s_cbranch_execz .LBB0_506
	s_mov_b32 s98, 0xf800000
	s_waitcnt vmcnt(0)
	v_mov_b32_e32 v206, v198
	v_mov_b32_e32 v207, v202
	v_mov_b32_e32 v202, v199
	v_mov_b32_e32 v198, v200
	v_mov_b32_e32 v199, v204
	v_mov_b32_e32 v204, v201
	v_pk_add_f32 v[200:201], v[206:207], v[202:203]
	v_pk_add_f32 v[198:199], v[198:199], v[204:205]
	s_nop 0
	v_pk_add_f32 v[198:199], v[200:201], v[198:199]
	s_nop 0
	v_add_f32_e32 v198, v198, v199
	v_fmamk_f32 v198, v198, 0x3a000000, v210
	v_mul_f32_e32 v199, 0x4f800000, v198
	v_cmp_gt_f32_e32 vcc, s98, v198
	s_nop 1
	v_cndmask_b32_e32 v198, v198, v199, vcc
	v_sqrt_f32_e32 v199, v198
	s_nop 0
	v_add_u32_e32 v200, -1, v199
	v_add_u32_e32 v201, 1, v199
	v_fma_f32 v202, -v200, v199, v198
	v_fma_f32 v203, -v201, v199, v198
	v_cmp_ge_f32_e64 s[98:99], 0, v202
	s_nop 1
	v_cndmask_b32_e64 v199, v199, v200, s[98:99]
	v_cmp_lt_f32_e64 s[98:99], 0, v203
	s_nop 1
	v_cndmask_b32_e64 v199, v199, v201, s[98:99]
	v_mul_f32_e32 v200, 0x37800000, v199
	v_cndmask_b32_e32 v199, v199, v200, vcc
	v_cmp_class_f32_e32 vcc, v198, v211
	s_nop 1
	v_cndmask_b32_e32 v198, v199, v198, vcc
	v_div_scale_f32 v199, s[98:99], v198, v198, 1.0
	v_rcp_f32_e32 v200, v199
	v_div_scale_f32 v201, vcc, 1.0, v198, 1.0
	v_fma_f32 v202, -v199, v200, 1.0
	v_fmac_f32_e32 v200, v202, v200
	v_mul_f32_e32 v202, v201, v200
	v_fma_f32 v203, -v199, v202, v201
	v_fmac_f32_e32 v202, v203, v200
	v_fma_f32 v199, -v199, v202, v201
	v_div_fmas_f32 v199, v199, v200, v202
	v_div_fixup_f32 v198, v199, v198, 1.0
	ds_write_b32 v167, v198
